# fox attention loop also staggered (mid-step barrier + one-barrier offset between virtual blocks, done-flag check moved to the skip path for the leading half)
# baseline (speedup 1.0000x reference)
; #define WAIT_ALL(S) asm volatile("s_waitcnt vmcnt(0)" : "+v"(rk0##S), "+v"(rk1##S), "+v"(rv0##S), "+v"(rv1##S), "+v"(rkr##S), "+v"(rck##S))
; template <int TYPE>
; DI void attn_item(KargPtr p, int b, int h, int qb, unsigned char* smem) {
;     ...
;         if (TYPE == 0) { const u32x4 one3 = hh == 0 ? (u32x4){0x3F803F80u, 0x00003F80u, 0u, 0u} : (u32x4){0u, 0u, 0u, 0u}; qfrag[KS - 1] = __builtin_bit_cast(bf16x8, one3); }
;     }
;     const bf16_t* Kg = (TYPE == 0 ? p->kf : TYPE == 1 ? p->kn : p->ks) + (size_t)b * SEQ * 512 + h * 64;
;     const bf16_t* Vg = (TYPE == 0 ? p->vtf : TYPE == 1 ? p->vtm : p->vts) + (size_t)(b * 8 + h) * 64 * SEQ;
;     const bf16_t* Krg = p->kr + (size_t)b * SEQ * 32;
;     const float* cumg = p->cum + (size_t)(b * 8 + h) * SEQ;
;     const int ntiles = 2 * qb + 2;
;     u32x4 rk0A, rk1A, rv0A, rv1A, rkrA, rk0B, rk1B, rv0B, rv1B, rkrB; float rckA = 0.f, rckB = 0.f;
;     { unsigned z_ = 0u; asm volatile("" : "+v"(z_)); rkrA = (u32x4){z_, z_, z_, z_}; rkrB = rkrA; }
;     const int ldrow = tid >> 3, ldch = tid & 7;
;     const int vpos = 16 * (ldch >> 1) + 4 * (ldch & 1);
;     ...
;     f32x16 o0, o1;
; #pragma unroll
;     for (int i = 0; i < 16; ++i) { o0[i] = 0.f; o1[i] = 0.f; }
;     float m = -1e30f, lsum = 0.f, carry = 0.f;
;     bool wdone = false;
;     float qbound = 0.f;
;     if (TYPE == 0) {
;         float ss = 0.f;
; #pragma unroll
;         for (int ks = 0; ks < 4; ++ks) { const u32x4 qq = __builtin_bit_cast(u32x4, qfrag[ks]);
; #pragma unroll
;             for (int e = 0; e < 4; ++e) { const float lo = __uint_as_float(qq[e] << 16), hi = __uint_as_float(qq[e] & 0xffff0000u); ss += lo * lo + hi * hi; } }
;         ss += __shfl_xor(ss, 32);
;         qbound = sqrtf(ss * p->kmax[b * 8 + h]) * 1.0201f;
;     }
;     ...
;     __syncthreads();
;     if (TYPE != 1 && tid < 16) flags[tid] = 0;
;     LOAD_TILE(A, TILE_OF(0));
;     WAIT_ALL(A);
;     STORE_TILE(A, 0);
;     LOAD_TILE(A, TILE_OF(1));
;     __syncthreads();
.LBB0_605:
	s_or_b64 exec, exec, s[10:11]
	v_cmp_gt_u32_e32 vcc, 32, v9
	v_mov_b32_e32 v0, 0x3f80
	s_add_i32 s6, s78, 2
	v_cndmask_b32_e32 v105, 0, v0, vcc
	v_mov_b32_e32 v0, 0x3f803f80
	v_cndmask_b32_e32 v104, 0, v0, vcc
	v_add_u32_e32 v0, s12, v173
	v_ashrrev_i32_e32 v1, 31, v0
	v_lshlrev_b64 v[12:13], 10, v[0:1]
	v_add_u32_e32 v0, 32, v0
	v_ashrrev_i32_e32 v1, 31, v0
	s_mov_b32 s13, s85
	v_writelane_b32 v255, s6, 22
	v_lshlrev_b32_e32 v154, 1, v10
	v_lshlrev_b64 v[0:1], 10, v[0:1]
	s_lshl_b64 s[6:7], s[12:13], 7
	v_mov_b32_e32 v156, v154
	v_mov_b32_e32 v157, v3
	v_lshl_add_u64 v[0:1], s[88:89], 0, v[0:1]
	s_add_u32 s6, s75, s6
	v_lshl_add_u64 v[12:13], s[88:89], 0, v[12:13]
	v_lshl_add_u64 v[0:1], v[0:1], 0, v[156:157]
	s_addc_u32 s7, s76, s7
	v_mul_f32_e32 v182, 0x3f8292a3, v11
	v_lshl_add_u64 v[10:11], v[12:13], 0, v[156:157]
	global_load_dwordx4 v[108:111], v[10:11], off
	global_load_dwordx4 v[112:115], v[0:1], off
	v_lshl_add_u64 v[0:1], v[132:133], 1, s[6:7]
	v_lshl_add_u64 v[0:1], v[0:1], 0, v[156:157]
	global_load_dwordx4 v[116:119], v[0:1], off
	v_lshl_add_u64 v[0:1], v[134:135], 1, s[6:7]
	s_lshl_b64 s[6:7], s[12:13], 2
	s_add_u32 s6, s77, s6
	v_lshl_add_u64 v[0:1], v[0:1], 0, v[156:157]
	s_addc_u32 s7, s96, s7
	v_mov_b32_e32 v158, v136
	v_mov_b32_e32 v159, v3
	global_load_dwordx4 v[120:123], v[0:1], off
	v_lshl_add_u64 v[0:1], s[6:7], 0, v[158:159]
	s_lshl_b32 s10, s25, 4
	global_load_dword v137, v[0:1], off
	v_mov_b32_e32 v0, s3
	s_add_i32 s10, s2, s10
	v_mad_u32_u24 v185, v4, s18, v0
	v_lshlrev_b32_e32 v183, 2, v8
	v_mad_u32_u24 v186, v4, s74, v0
	v_lshl_add_u32 v187, v5, 2, s10
	v_add_u32_e32 v0, v6, v4
	s_lshl_b32 s10, s23, 7
	s_lshl_b32 s11, s22, 9
	v_mov_b32_e32 v14, v3
	v_mov_b32_e32 v15, v3
	v_cmp_eq_u32_e64 s[6:7], 63, v7
	v_cmp_eq_u32_e64 s[8:9], 0, v9
	v_sub_u32_e32 v188, v0, v183
	s_or_b32 s10, s10, s11
	v_mov_b32_e32 v0, v3
	v_mov_b32_e32 v1, v3
	v_mov_b32_e32 v2, v3
	v_mov_b32_e32 v4, v3
	v_mov_b32_e32 v5, v3
	v_mov_b32_e32 v6, v3
	v_mov_b32_e32 v7, v3
	v_mov_b32_e32 v8, v3
	v_mov_b32_e32 v9, v3
	v_mov_b32_e32 v10, v3
	v_mov_b32_e32 v11, v3
	v_mov_b32_e32 v12, v3
	v_mov_b32_e32 v13, v3
	v_mov_b64_e32 v[30:31], v[14:15]
	v_mov_b64_e32 v[46:47], v[14:15]
	s_mov_b32 s84, 0
	v_mov_b32_e32 v106, v3
	v_mov_b32_e32 v107, v3
	v_or_b32_e32 v184, 31, v172
	s_add_i32 s97, s79, 0x24810
	s_add_i32 s33, s79, 0x24820
	s_add_i32 s79, s79, 0x24830
	s_sub_i32 s74, 0xfbf, s10
	v_mov_b32_e32 v160, 0xf149f2ca
	v_mov_b32_e32 v191, 0
	v_mov_b32_e32 v189, 0
	v_mov_b64_e32 v[28:29], v[12:13]
	v_mov_b64_e32 v[26:27], v[10:11]
	v_mov_b64_e32 v[24:25], v[8:9]
	v_mov_b64_e32 v[22:23], v[6:7]
	v_mov_b64_e32 v[20:21], v[4:5]
	v_mov_b64_e32 v[18:19], v[2:3]
	v_mov_b64_e32 v[16:17], v[0:1]
	v_mov_b64_e32 v[44:45], v[12:13]
	v_mov_b64_e32 v[42:43], v[10:11]
	v_mov_b64_e32 v[40:41], v[8:9]
	v_mov_b64_e32 v[38:39], v[6:7]
	v_mov_b64_e32 v[36:37], v[4:5]
	v_mov_b64_e32 v[34:35], v[2:3]
	v_mov_b64_e32 v[32:33], v[0:1]
	s_waitcnt lgkmcnt(0)
	s_barrier
	s_cmp_eq_u32 s3, 0
	s_cbranch_scc1 .Lfox_nostag_in
	s_barrier

; #define WAIT_ALL(S) asm volatile("s_waitcnt vmcnt(0)" : "+v"(rk0##S), "+v"(rk1##S), "+v"(rv0##S), "+v"(rv1##S), "+v"(rkr##S), "+v"(rck##S))
; #define WAIT_OLD(S) do { if (TYPE == 2) asm volatile("s_waitcnt vmcnt(4)" : "+v"(rk0##S), "+v"(rk1##S), "+v"(rv0##S), "+v"(rv1##S), "+v"(rkr##S), "+v"(rck##S)); \
;         else asm volatile("s_waitcnt vmcnt(5)" : "+v"(rk0##S), "+v"(rk1##S), "+v"(rv0##S), "+v"(rv1##S), "+v"(rkr##S), "+v"(rck##S)); } while (0)
; #define SB_FLAGS(N_) do { if (TYPE != 1) { if (TYPE == 2) wdone = (__all(carry < -170.f) != 0); if (lane == 0) flags[((N_) & 1) * 8 + w8] = wdone ? 1u : 0u; } } while (0)
; template <int TYPE>
; DI void attn_item(KargPtr p, int b, int h, int qb, unsigned char* smem) {
;     ...
;     __syncthreads();
;     if (TYPE != 1 && tid < 16) flags[tid] = 0;
;     LOAD_TILE(A, TILE_OF(0));
;     WAIT_ALL(A);
;     STORE_TILE(A, 0);
;     LOAD_TILE(A, TILE_OF(1));
;     __syncthreads();
;     for (int n = 0; n < ntiles; n += 2) {
;         LOAD_TILE(B, TILE_OF(n + 2));
;         __builtin_amdgcn_sched_barrier(0);
;         compute(TILE_OF(n), 0);
;         __builtin_amdgcn_sched_barrier(0);
;         WAIT_OLD(A);
;         STORE_TILE(A, 1);
;         SB_FLAGS(n);
;         __syncthreads();
;         if (SB_DONE(n)) break;
;         if (n + 1 >= ntiles) break;
;         LOAD_TILE(A, TILE_OF(n + 3));
;         __builtin_amdgcn_sched_barrier(0);
;         compute(TILE_OF(n + 1), 1);
;         __builtin_amdgcn_sched_barrier(0);
;         WAIT_OLD(B);
;         STORE_TILE(B, 0);
;         SB_FLAGS(n + 1);
;         __syncthreads();
;         if (SB_DONE(n + 1)) break;
;     }
.LBB0_606:
	s_or_b64 exec, exec, s[10:11]
	v_mov_b32_e32 v0, s2
	s_waitcnt lgkmcnt(0)
	s_barrier
	s_cmp_eq_u32 s3, 0
	s_cbranch_scc1 .LBB0_608
	ds_read_b128 v[48:51], v0
	v_mov_b32_e32 v1, s97
	s_waitcnt lgkmcnt(0)
	v_and_b32_e32 v0, v49, v48
	v_and_b32_e32 v0, v0, v50
	v_and_b32_e32 v0, v0, v51
	ds_read_b128 v[48:51], v1
	s_waitcnt lgkmcnt(0)
	v_and_b32_e32 v0, v0, v48
	v_and_b32_e32 v0, v0, v49
	v_and_b32_e32 v0, v0, v50
	v_and_b32_e32 v0, v0, v51
	v_cmp_ne_u32_e32 vcc, 0, v0
	s_cbranch_vccz .LBB0_608
	s_cbranch_execz .LBB0_620
	s_branch .LBB0_564
.Lfox_skip_a:
	s_barrier
	s_cmp_lg_u32 s3, 0
	s_cbranch_scc1 .LBB0_626
	s_mov_b64 exec, -1
	v_mov_b32_e32 v225, s33
	v_mov_b32_e32 v234, s79
	ds_read_b128 v[226:229], v225
	ds_read_b128 v[230:233], v234
	s_waitcnt lgkmcnt(0)
	v_and_b32_e32 v225, v226, v227
	v_and_b32_e32 v225, v225, v228
	v_and_b32_e32 v225, v225, v229
	v_and_b32_e32 v225, v225, v230
	v_and_b32_e32 v225, v225, v231
	v_and_b32_e32 v225, v225, v232
	v_and_b32_e32 v225, v225, v233
	v_cmp_ne_u32_e32 vcc, 0, v225
	s_cbranch_vccz .LBB0_626
	s_branch .LBB0_564
.Lfox_skip_b:
	s_barrier
	s_cmp_lg_u32 s3, 0
	s_cbranch_scc1 .LBB0_614
	s_mov_b64 exec, -1
	v_mov_b32_e32 v225, s2
	v_mov_b32_e32 v234, s97
	ds_read_b128 v[226:229], v225
	ds_read_b128 v[230:233], v234
	s_waitcnt lgkmcnt(0)
	v_and_b32_e32 v225, v226, v227
	v_and_b32_e32 v225, v225, v228
	v_and_b32_e32 v225, v225, v229
	v_and_b32_e32 v225, v225, v230
	v_and_b32_e32 v225, v225, v231
	v_and_b32_e32 v225, v225, v232
	v_and_b32_e32 v225, v225, v233
	v_cmp_ne_u32_e32 vcc, 0, v225
	s_cbranch_vccz .LBB0_614
	s_branch .LBB0_564
.Lfox_exit_b:
	s_cmp_lg_u32 s3, 0
	s_cbranch_scc1 .LBB0_564
	s_barrier
	s_branch .LBB0_564

; #define MFMA(a, b, c) __builtin_amdgcn_mfma_f32_32x32x16_bf16((a), (b), (c), 0, 0, 0)
; DI float fexp2(float x) { return __builtin_amdgcn_exp2f(x); }
; template <int TYPE>
; DI void attn_item(KargPtr p, int b, int h, int qb, unsigned char* smem) {
;     ...
;                 float mx = s0[0];
; #pragma unroll
;                 for (int i = 1; i < 16; ++i) mx = fmaxf(mx, s0[i]);
; #pragma unroll
;                 for (int i = 0; i < 16; ++i) mx = fmaxf(mx, s1[i]);
;                 mx = fmaxf(mx, __shfl_xor(mx, 32));
;                 const float mnew = fmaxf(m, mx);
;                 const float alpha = fexp2(m - mnew);
;                 m = mnew;
;                 float ps = 0.f;
; #pragma unroll
;                 for (int i = 0; i < 16; i += 2) {
;                     const f32x2_t mm = {mnew, mnew};
;                     const f32x2_t d0 = (f32x2_t){s0[i], s0[i + 1]} - mm, d1 = (f32x2_t){s1[i], s1[i + 1]} - mm;
;                     s0[i] = fexp2(d0[0]); s0[i + 1] = fexp2(d0[1]); s1[i] = fexp2(d1[0]); s1[i + 1] = fexp2(d1[1]);
;                     ps += (s0[i] + s0[i + 1]) + (s1[i] + s1[i + 1]);
;                 }
;                 lsum = lsum * alpha + ps;
; #pragma unroll
;                 for (int i = 0; i < 16; ++i) { o0[i] *= alpha; o1[i] *= alpha; }
;     ...
; #pragma unroll
;             for (int s2 = 0; s2 < 2; ++s2) {
;                 unsigned pk0[4], pk1[4];
; #pragma unroll
;                 for (int j = 0; j < 4; ++j) { pk0[j] = pack_bf16(s0[8 * s2 + 2 * j], s0[8 * s2 + 2 * j + 1]); pk1[j] = pack_bf16(s1[8 * s2 + 2 * j], s1[8 * s2 + 2 * j + 1]); }
;                 const uint4 u0 = make_uint4(pk0[0], pk0[1], pk0[2], pk0[3]), u1 = make_uint4(pk1[0], pk1[1], pk1[2], pk1[3]);
;                 const bf16x8 pf0 = __builtin_bit_cast(bf16x8, u0), pf1 = __builtin_bit_cast(bf16x8, u1);
;                 const bf16x8 v00 = *(const bf16x8*)(vb + r * VROWB + (16 * s2 + 8 * hh) * 2);
;                 const bf16x8 v01 = *(const bf16x8*)(vb + (32 + r) * VROWB + (16 * s2 + 8 * hh) * 2);
;                 const bf16x8 v10 = *(const bf16x8*)(vb + r * VROWB + (32 + 16 * s2 + 8 * hh) * 2);
;                 const bf16x8 v11 = *(const bf16x8*)(vb + (32 + r) * VROWB + (32 + 16 * s2 + 8 * hh) * 2);
;                 o0 = MFMA(v00, pf0, o0); o1 = MFMA(v01, pf0, o1);
;                 o0 = MFMA(v10, pf1, o0); o1 = MFMA(v11, pf1, o1);
;             }
.LBB0_613:
	s_or_b64 exec, exec, s[86:87]
	s_nop 5
	v_max_f32_e32 v0, v49, v49
	v_max_f32_e32 v1, v48, v48
	v_max_f32_e32 v0, v1, v0
	v_max3_f32 v0, v0, v50, v51
	v_max3_f32 v0, v0, v52, v53
	v_max3_f32 v0, v0, v54, v55
	v_max3_f32 v0, v0, v56, v57
	v_max3_f32 v0, v0, v58, v59
	v_max3_f32 v0, v0, v60, v61
	v_max3_f32 v0, v0, v62, v63
	v_max3_f32 v0, v0, v64, v65
	v_max3_f32 v0, v0, v66, v67
	v_max3_f32 v0, v0, v68, v69
	v_max3_f32 v0, v0, v70, v71
	v_max3_f32 v0, v0, v72, v73
	v_max3_f32 v0, v0, v74, v75
	v_max3_f32 v0, v0, v76, v77
	v_max3_f32 v0, v0, v78, v79
	v_mov_b32_e32 v1, v0
	v_mov_b32_e32 v225, v0
	s_nop 1
	v_permlane32_swap_b32_e32 v1, v225
	v_max3_f32 v0, v160, v1, v225
	v_pk_add_f32 v[48:49], v[48:49], v[0:1] op_sel_hi:[1,0] neg_lo:[0,1] neg_hi:[0,1]
	v_pk_add_f32 v[64:65], v[64:65], v[0:1] op_sel_hi:[1,0] neg_lo:[0,1] neg_hi:[0,1]
	v_exp_f32_e32 v161, v48
	v_exp_f32_e32 v165, v49
	v_pk_add_f32 v[48:49], v[50:51], v[0:1] op_sel_hi:[1,0] neg_lo:[0,1] neg_hi:[0,1]
	v_pk_add_f32 v[50:51], v[66:67], v[0:1] op_sel_hi:[1,0] neg_lo:[0,1] neg_hi:[0,1]
	v_sub_f32_e32 v2, v160, v0
	v_exp_f32_e32 v163, v64
	v_exp_f32_e32 v167, v65
	v_exp_f32_e32 v160, v48
	v_exp_f32_e32 v164, v49
	v_exp_f32_e32 v162, v50
	v_exp_f32_e32 v166, v51
	v_exp_f32_e32 v2, v2
	v_pk_add_f32 v[48:49], v[164:165], v[160:161]
	v_pk_add_f32 v[50:51], v[166:167], v[162:163]
	s_nop 0
	v_pk_add_f32 v[48:49], v[50:51], v[48:49]
	v_pk_mul_f32 v[46:47], v[46:47], v[2:3] op_sel_hi:[1,0]
	v_add_f32_e32 v1, 0, v49
	v_pk_add_f32 v[50:51], v[52:53], v[0:1] op_sel_hi:[1,0] neg_lo:[0,1] neg_hi:[0,1]
	v_pk_add_f32 v[52:53], v[68:69], v[0:1] op_sel_hi:[1,0] neg_lo:[0,1] neg_hi:[0,1]
	v_exp_f32_e32 v169, v50
	v_exp_f32_e32 v171, v51
	v_exp_f32_e32 v168, v52
	v_exp_f32_e32 v170, v53
	v_pk_add_f32 v[52:53], v[54:55], v[0:1] op_sel_hi:[1,0] neg_lo:[0,1] neg_hi:[0,1]
	v_pk_add_f32 v[54:55], v[70:71], v[0:1] op_sel_hi:[1,0] neg_lo:[0,1] neg_hi:[0,1]
	v_exp_f32_e32 v138, v52
	v_pk_add_f32 v[50:51], v[170:171], v[168:169]
	v_exp_f32_e32 v139, v53
	v_pk_add_f32 v[50:51], v[50:51], v[50:51] op_sel_hi:[0,1]
	v_exp_f32_e32 v140, v54
	v_exp_f32_e32 v141, v55
	v_pk_add_f32 v[56:57], v[56:57], v[0:1] op_sel_hi:[1,0] neg_lo:[0,1] neg_hi:[0,1]
	v_pk_add_f32 v[64:65], v[72:73], v[0:1] op_sel_hi:[1,0] neg_lo:[0,1] neg_hi:[0,1]
	s_barrier
	v_add_f32_e32 v49, v48, v1
	v_exp_f32_e32 v48, v56
	v_exp_f32_e32 v50, v57
	v_exp_f32_e32 v52, v64
	v_exp_f32_e32 v54, v65
	v_add_f32_e32 v53, v139, v138
	v_add_f32_e32 v55, v141, v140
	v_pk_add_f32 v[56:57], v[50:51], v[48:49]
	v_pk_add_f32 v[64:65], v[54:55], v[52:53]
	v_pk_add_f32 v[66:67], v[74:75], v[0:1] op_sel_hi:[1,0] neg_lo:[0,1] neg_hi:[0,1]
	v_pk_add_f32 v[56:57], v[64:65], v[56:57]
	v_pk_add_f32 v[64:65], v[58:59], v[0:1] op_sel_hi:[1,0] neg_lo:[0,1] neg_hi:[0,1]
	v_exp_f32_e32 v58, v66
	v_exp_f32_e32 v59, v64
	v_exp_f32_e32 v65, v65
	v_exp_f32_e32 v64, v67
	v_pk_add_f32 v[60:61], v[60:61], v[0:1] op_sel_hi:[1,0] neg_lo:[0,1] neg_hi:[0,1]
	v_pk_add_f32 v[68:69], v[76:77], v[0:1] op_sel_hi:[1,0] neg_lo:[0,1] neg_hi:[0,1]
	v_pk_add_f32 v[56:57], v[56:57], v[56:57] op_sel_hi:[0,1]
	v_pk_add_f32 v[66:67], v[64:65], v[58:59]
	v_exp_f32_e32 v51, v60
	v_pk_add_f32 v[66:67], v[66:67], v[66:67] op_sel_hi:[0,1]
	v_exp_f32_e32 v55, v61
	v_exp_f32_e32 v146, v68
	v_exp_f32_e32 v147, v69
	v_pk_add_f32 v[62:63], v[62:63], v[0:1] op_sel_hi:[1,0] neg_lo:[0,1] neg_hi:[0,1]
	v_pk_add_f32 v[70:71], v[78:79], v[0:1] op_sel_hi:[1,0] neg_lo:[0,1] neg_hi:[0,1]
	v_exp_f32_e32 v56, v62
	v_exp_f32_e32 v66, v63
	v_exp_f32_e32 v60, v70
	v_exp_f32_e32 v68, v71
	v_add_f32_e32 v61, v55, v51
	v_add_f32_e32 v69, v147, v146
	v_pk_add_f32 v[62:63], v[66:67], v[56:57]
	v_pk_add_f32 v[70:71], v[68:69], v[60:61]
	v_pk_mul_f32 v[44:45], v[44:45], v[2:3] op_sel_hi:[1,0]
	v_pk_add_f32 v[62:63], v[70:71], v[62:63]
	v_pk_mul_f32 v[42:43], v[42:43], v[2:3] op_sel_hi:[1,0]
	v_add_f32_e32 v1, v62, v63
	v_fmac_f32_e32 v1, v191, v2
	v_pk_mul_f32 v[40:41], v[40:41], v[2:3] op_sel_hi:[1,0]
	v_pk_mul_f32 v[38:39], v[38:39], v[2:3] op_sel_hi:[1,0]
	v_pk_mul_f32 v[36:37], v[36:37], v[2:3] op_sel_hi:[1,0]
	v_pk_mul_f32 v[34:35], v[34:35], v[2:3] op_sel_hi:[1,0]
	v_pk_mul_f32 v[32:33], v[32:33], v[2:3] op_sel_hi:[1,0]
	v_pk_mul_f32 v[30:31], v[30:31], v[2:3] op_sel_hi:[1,0]
	v_pk_mul_f32 v[28:29], v[28:29], v[2:3] op_sel_hi:[1,0]
	v_pk_mul_f32 v[26:27], v[26:27], v[2:3] op_sel_hi:[1,0]
	v_pk_mul_f32 v[24:25], v[24:25], v[2:3] op_sel_hi:[1,0]
	v_pk_mul_f32 v[22:23], v[22:23], v[2:3] op_sel_hi:[1,0]
	v_pk_mul_f32 v[20:21], v[20:21], v[2:3] op_sel_hi:[1,0]
	v_pk_mul_f32 v[18:19], v[18:19], v[2:3] op_sel_hi:[1,0]
	v_pk_mul_f32 v[16:17], v[16:17], v[2:3] op_sel_hi:[1,0]
	v_add_u32_e32 v2, v186, v130
	v_cvt_pk_bf16_f32 v70, v161, v165
	v_cvt_pk_bf16_f32 v74, v163, v167
	v_cvt_pk_bf16_f32 v71, v160, v164
	v_cvt_pk_bf16_f32 v75, v162, v166
	v_cvt_pk_bf16_f32 v73, v138, v139
	v_cvt_pk_bf16_f32 v77, v140, v141
	ds_read_b128 v[138:141], v2 offset:36608
	ds_read_b128 v[142:145], v2 offset:32064
	ds_read_b128 v[150:153], v2 offset:36672
	ds_read_b128 v[160:163], v2 offset:32000
	ds_read_b128 v[164:167], v2 offset:32032
	v_cvt_pk_bf16_f32 v72, v169, v171
	v_cvt_pk_bf16_f32 v76, v168, v170
	v_cvt_pk_bf16_f32 v48, v48, v50
	s_waitcnt lgkmcnt(1)
	v_mfma_f32_32x32x16_bf16 v[32:47], v[160:163], v[70:73], v[32:47]
	v_cvt_pk_bf16_f32 v49, v59, v65
	v_cvt_pk_bf16_f32 v53, v58, v64
	v_cvt_pk_bf16_f32 v50, v51, v55
	v_cvt_pk_bf16_f32 v51, v56, v66
	v_cvt_pk_bf16_f32 v55, v60, v68
	ds_read_b128 v[56:59], v2 offset:36640
	ds_read_b128 v[60:63], v2 offset:32096
	ds_read_b128 v[64:67], v2 offset:36704
	v_cvt_pk_bf16_f32 v52, v52, v54
	v_mfma_f32_32x32x16_bf16 v[16:31], v[138:141], v[70:73], v[16:31]
	v_cvt_pk_bf16_f32 v54, v146, v147
	v_mov_b32_e32 v191, v1
	v_mov_b32_e32 v160, v0
	v_mfma_f32_32x32x16_bf16 v[32:47], v[142:145], v[74:77], v[32:47]
	v_mfma_f32_32x32x16_bf16 v[16:31], v[150:153], v[74:77], v[16:31]
	s_waitcnt lgkmcnt(3)
	v_mfma_f32_32x32x16_bf16 v[32:47], v[164:167], v[48:51], v[32:47]
	s_waitcnt lgkmcnt(2)
	v_mfma_f32_32x32x16_bf16 v[16:31], v[56:59], v[48:51], v[16:31]
	s_waitcnt lgkmcnt(1)
	v_mfma_f32_32x32x16_bf16 v[32:47], v[60:63], v[52:55], v[32:47]
	s_waitcnt lgkmcnt(0)
	v_mfma_f32_32x32x16_bf16 v[16:31], v[64:67], v[52:55], v[16:31]

; #define WAIT_OLD(S) do { if (TYPE == 2) asm volatile("s_waitcnt vmcnt(4)" : "+v"(rk0##S), "+v"(rk1##S), "+v"(rv0##S), "+v"(rv1##S), "+v"(rkr##S), "+v"(rck##S)); \
;         else asm volatile("s_waitcnt vmcnt(5)" : "+v"(rk0##S), "+v"(rk1##S), "+v"(rv0##S), "+v"(rv1##S), "+v"(rkr##S), "+v"(rck##S)); } while (0)
; #define SB_FLAGS(N_) do { if (TYPE != 1) { if (TYPE == 2) wdone = (__all(carry < -170.f) != 0); if (lane == 0) flags[((N_) & 1) * 8 + w8] = wdone ? 1u : 0u; } } while (0)
; template <int TYPE>
; DI void attn_item(KargPtr p, int b, int h, int qb, unsigned char* smem) {
;     ...
;         WAIT_OLD(B);
;         STORE_TILE(B, 0);
;         SB_FLAGS(n + 1);
;         __syncthreads();
;         if (SB_DONE(n + 1)) break;
;     }
.LBB0_617:
	s_or_b64 exec, exec, s[10:11]
	s_and_saveexec_b64 s[10:11], s[8:9]
	v_and_b32_e32 v0, 0xff, v189
	ds_write_b32 v187, v0 offset:32
	s_or_b64 exec, exec, s[10:11]
	v_mov_b32_e32 v0, s33
	s_waitcnt lgkmcnt(0)
	s_barrier
	ds_read_b128 v[48:51], v0
	v_mov_b32_e32 v1, s79
	s_xor_b64 s[10:11], s[82:83], -1
	v_add_u32_e32 v188, 0x80, v188
	s_addk_i32 s74, 0xff80
	s_waitcnt lgkmcnt(0)
	v_and_b32_e32 v0, v49, v48
	v_and_b32_e32 v0, v0, v50
	v_and_b32_e32 v0, v0, v51
	ds_read_b128 v[48:51], v1
	s_add_i32 s84, s84, -1
	s_waitcnt lgkmcnt(0)
	v_and_b32_e32 v0, v0, v48
	v_and_b32_e32 v0, v0, v49
	v_and_b32_e32 v0, v0, v50
	v_and_b32_e32 v0, v0, v51
	v_cmp_ne_u32_e32 vcc, 0, v0
	s_cmp_eq_u32 s3, 0
	s_cselect_b64 s[98:99], 0, -1
	s_and_b64 vcc, vcc, s[98:99]
	s_or_b64 s[10:11], vcc, s[10:11]
	s_and_b64 vcc, exec, s[10:11]
	s_cbranch_vccnz .Lfox_exit_b

; #define MFMA(a, b, c) __builtin_amdgcn_mfma_f32_32x32x16_bf16((a), (b), (c), 0, 0, 0)
; DI float fexp2(float x) { return __builtin_amdgcn_exp2f(x); }
; template <int TYPE>
; DI void attn_item(KargPtr p, int b, int h, int qb, unsigned char* smem) {
;     ...
;                 float mx = s0[0];
; #pragma unroll
;                 for (int i = 1; i < 16; ++i) mx = fmaxf(mx, s0[i]);
; #pragma unroll
;                 for (int i = 0; i < 16; ++i) mx = fmaxf(mx, s1[i]);
;                 mx = fmaxf(mx, __shfl_xor(mx, 32));
;                 const float mnew = fmaxf(m, mx);
;                 const float alpha = fexp2(m - mnew);
;                 m = mnew;
;                 float ps = 0.f;
; #pragma unroll
;                 for (int i = 0; i < 16; i += 2) {
;                     const f32x2_t mm = {mnew, mnew};
;                     const f32x2_t d0 = (f32x2_t){s0[i], s0[i + 1]} - mm, d1 = (f32x2_t){s1[i], s1[i + 1]} - mm;
;                     s0[i] = fexp2(d0[0]); s0[i + 1] = fexp2(d0[1]); s1[i] = fexp2(d1[0]); s1[i + 1] = fexp2(d1[1]);
;                     ps += (s0[i] + s0[i + 1]) + (s1[i] + s1[i + 1]);
;                 }
;                 lsum = lsum * alpha + ps;
; #pragma unroll
;                 for (int i = 0; i < 16; ++i) { o0[i] *= alpha; o1[i] *= alpha; }
;     ...
; #pragma unroll
;             for (int s2 = 0; s2 < 2; ++s2) {
;                 unsigned pk0[4], pk1[4];
; #pragma unroll
;                 for (int j = 0; j < 4; ++j) { pk0[j] = pack_bf16(s0[8 * s2 + 2 * j], s0[8 * s2 + 2 * j + 1]); pk1[j] = pack_bf16(s1[8 * s2 + 2 * j], s1[8 * s2 + 2 * j + 1]); }
;                 const uint4 u0 = make_uint4(pk0[0], pk0[1], pk0[2], pk0[3]), u1 = make_uint4(pk1[0], pk1[1], pk1[2], pk1[3]);
;                 const bf16x8 pf0 = __builtin_bit_cast(bf16x8, u0), pf1 = __builtin_bit_cast(bf16x8, u1);
;                 const bf16x8 v00 = *(const bf16x8*)(vb + r * VROWB + (16 * s2 + 8 * hh) * 2);
;                 const bf16x8 v01 = *(const bf16x8*)(vb + (32 + r) * VROWB + (16 * s2 + 8 * hh) * 2);
;                 const bf16x8 v10 = *(const bf16x8*)(vb + r * VROWB + (32 + 16 * s2 + 8 * hh) * 2);
;                 const bf16x8 v11 = *(const bf16x8*)(vb + (32 + r) * VROWB + (32 + 16 * s2 + 8 * hh) * 2);
;                 o0 = MFMA(v00, pf0, o0); o1 = MFMA(v01, pf0, o1);
;                 o0 = MFMA(v10, pf1, o0); o1 = MFMA(v11, pf1, o1);
;             }
.LBB0_625:
	s_or_b64 exec, exec, s[86:87]
	s_nop 5
	v_max_f32_e32 v0, v49, v49
	v_max_f32_e32 v1, v48, v48
	v_max_f32_e32 v0, v1, v0
	v_max3_f32 v0, v0, v50, v51
	v_max3_f32 v0, v0, v52, v53
	v_max3_f32 v0, v0, v54, v55
	v_max3_f32 v0, v0, v56, v57
	v_max3_f32 v0, v0, v58, v59
	v_max3_f32 v0, v0, v60, v61
	v_max3_f32 v0, v0, v62, v63
	v_max3_f32 v0, v0, v64, v65
	v_max3_f32 v0, v0, v66, v67
	v_max3_f32 v0, v0, v68, v69
	v_max3_f32 v0, v0, v70, v71
	v_max3_f32 v0, v0, v72, v73
	v_max3_f32 v0, v0, v74, v75
	v_max3_f32 v0, v0, v76, v77
	v_max3_f32 v0, v0, v78, v79
	v_mov_b32_e32 v1, v0
	v_mov_b32_e32 v225, v0
	s_nop 1
	v_permlane32_swap_b32_e32 v1, v225
	v_max3_f32 v0, v160, v1, v225
	v_pk_add_f32 v[48:49], v[48:49], v[0:1] op_sel_hi:[1,0] neg_lo:[0,1] neg_hi:[0,1]
	v_pk_add_f32 v[64:65], v[64:65], v[0:1] op_sel_hi:[1,0] neg_lo:[0,1] neg_hi:[0,1]
	v_exp_f32_e32 v161, v48
	v_exp_f32_e32 v165, v49
	v_pk_add_f32 v[48:49], v[50:51], v[0:1] op_sel_hi:[1,0] neg_lo:[0,1] neg_hi:[0,1]
	v_pk_add_f32 v[50:51], v[66:67], v[0:1] op_sel_hi:[1,0] neg_lo:[0,1] neg_hi:[0,1]
	v_sub_f32_e32 v2, v160, v0
	v_exp_f32_e32 v163, v64
	v_exp_f32_e32 v167, v65
	v_exp_f32_e32 v160, v48
	v_exp_f32_e32 v164, v49
	v_exp_f32_e32 v162, v50
	v_exp_f32_e32 v166, v51
	v_exp_f32_e32 v2, v2
	v_pk_add_f32 v[48:49], v[164:165], v[160:161]
	v_pk_add_f32 v[50:51], v[166:167], v[162:163]
	s_nop 0
	v_pk_add_f32 v[48:49], v[50:51], v[48:49]
	v_pk_mul_f32 v[46:47], v[46:47], v[2:3] op_sel_hi:[1,0]
	v_add_f32_e32 v1, 0, v49
	v_pk_add_f32 v[50:51], v[52:53], v[0:1] op_sel_hi:[1,0] neg_lo:[0,1] neg_hi:[0,1]
	v_pk_add_f32 v[52:53], v[68:69], v[0:1] op_sel_hi:[1,0] neg_lo:[0,1] neg_hi:[0,1]
	v_exp_f32_e32 v169, v50
	v_exp_f32_e32 v171, v51
	v_exp_f32_e32 v168, v52
	v_exp_f32_e32 v170, v53
	v_pk_add_f32 v[52:53], v[54:55], v[0:1] op_sel_hi:[1,0] neg_lo:[0,1] neg_hi:[0,1]
	v_pk_add_f32 v[54:55], v[70:71], v[0:1] op_sel_hi:[1,0] neg_lo:[0,1] neg_hi:[0,1]
	v_exp_f32_e32 v138, v52
	v_pk_add_f32 v[50:51], v[170:171], v[168:169]
	v_exp_f32_e32 v139, v53
	v_pk_add_f32 v[50:51], v[50:51], v[50:51] op_sel_hi:[0,1]
	v_exp_f32_e32 v140, v54
	v_exp_f32_e32 v141, v55
	v_pk_add_f32 v[56:57], v[56:57], v[0:1] op_sel_hi:[1,0] neg_lo:[0,1] neg_hi:[0,1]
	v_pk_add_f32 v[64:65], v[72:73], v[0:1] op_sel_hi:[1,0] neg_lo:[0,1] neg_hi:[0,1]
	s_barrier
	v_add_f32_e32 v49, v48, v1
	v_exp_f32_e32 v48, v56
	v_exp_f32_e32 v50, v57
	v_exp_f32_e32 v52, v64
	v_exp_f32_e32 v54, v65
	v_add_f32_e32 v53, v139, v138
	v_add_f32_e32 v55, v141, v140
	v_pk_add_f32 v[56:57], v[50:51], v[48:49]
	v_pk_add_f32 v[64:65], v[54:55], v[52:53]
	v_pk_add_f32 v[66:67], v[74:75], v[0:1] op_sel_hi:[1,0] neg_lo:[0,1] neg_hi:[0,1]
	v_pk_add_f32 v[56:57], v[64:65], v[56:57]
	v_pk_add_f32 v[64:65], v[58:59], v[0:1] op_sel_hi:[1,0] neg_lo:[0,1] neg_hi:[0,1]
	v_exp_f32_e32 v58, v66
	v_exp_f32_e32 v59, v64
	v_exp_f32_e32 v65, v65
	v_exp_f32_e32 v64, v67
	v_pk_add_f32 v[60:61], v[60:61], v[0:1] op_sel_hi:[1,0] neg_lo:[0,1] neg_hi:[0,1]
	v_pk_add_f32 v[68:69], v[76:77], v[0:1] op_sel_hi:[1,0] neg_lo:[0,1] neg_hi:[0,1]
	v_pk_add_f32 v[56:57], v[56:57], v[56:57] op_sel_hi:[0,1]
	v_pk_add_f32 v[66:67], v[64:65], v[58:59]
	v_exp_f32_e32 v51, v60
	v_pk_add_f32 v[66:67], v[66:67], v[66:67] op_sel_hi:[0,1]
	v_exp_f32_e32 v55, v61
	v_exp_f32_e32 v146, v68
	v_exp_f32_e32 v147, v69
	v_pk_add_f32 v[62:63], v[62:63], v[0:1] op_sel_hi:[1,0] neg_lo:[0,1] neg_hi:[0,1]
	v_pk_add_f32 v[70:71], v[78:79], v[0:1] op_sel_hi:[1,0] neg_lo:[0,1] neg_hi:[0,1]
	v_exp_f32_e32 v56, v62
	v_exp_f32_e32 v66, v63
	v_exp_f32_e32 v60, v70
	v_exp_f32_e32 v68, v71
	v_add_f32_e32 v61, v55, v51
	v_add_f32_e32 v69, v147, v146
	v_pk_add_f32 v[62:63], v[66:67], v[56:57]
	v_pk_add_f32 v[70:71], v[68:69], v[60:61]
	v_pk_mul_f32 v[44:45], v[44:45], v[2:3] op_sel_hi:[1,0]
	v_pk_add_f32 v[62:63], v[70:71], v[62:63]
	v_pk_mul_f32 v[42:43], v[42:43], v[2:3] op_sel_hi:[1,0]
	v_add_f32_e32 v1, v62, v63
	v_fmac_f32_e32 v1, v191, v2
	v_pk_mul_f32 v[40:41], v[40:41], v[2:3] op_sel_hi:[1,0]
	v_pk_mul_f32 v[38:39], v[38:39], v[2:3] op_sel_hi:[1,0]
	v_pk_mul_f32 v[36:37], v[36:37], v[2:3] op_sel_hi:[1,0]
	v_pk_mul_f32 v[34:35], v[34:35], v[2:3] op_sel_hi:[1,0]
	v_pk_mul_f32 v[32:33], v[32:33], v[2:3] op_sel_hi:[1,0]
	v_pk_mul_f32 v[30:31], v[30:31], v[2:3] op_sel_hi:[1,0]
	v_pk_mul_f32 v[28:29], v[28:29], v[2:3] op_sel_hi:[1,0]
	v_pk_mul_f32 v[26:27], v[26:27], v[2:3] op_sel_hi:[1,0]
	v_pk_mul_f32 v[24:25], v[24:25], v[2:3] op_sel_hi:[1,0]
	v_pk_mul_f32 v[22:23], v[22:23], v[2:3] op_sel_hi:[1,0]
	v_pk_mul_f32 v[20:21], v[20:21], v[2:3] op_sel_hi:[1,0]
	v_pk_mul_f32 v[18:19], v[18:19], v[2:3] op_sel_hi:[1,0]
	v_pk_mul_f32 v[16:17], v[16:17], v[2:3] op_sel_hi:[1,0]
	v_add_u32_e32 v2, v186, v130
	v_cvt_pk_bf16_f32 v70, v161, v165
	v_cvt_pk_bf16_f32 v74, v163, v167
	v_cvt_pk_bf16_f32 v71, v160, v164
	v_cvt_pk_bf16_f32 v75, v162, v166
	v_cvt_pk_bf16_f32 v73, v138, v139
	v_cvt_pk_bf16_f32 v77, v140, v141
	ds_read_b128 v[138:141], v2 offset:15872
	ds_read_b128 v[142:145], v2 offset:11328
	ds_read_b128 v[150:153], v2 offset:15936
	ds_read_b128 v[160:163], v2 offset:11264
	ds_read_b128 v[164:167], v2 offset:11296
	v_cvt_pk_bf16_f32 v72, v169, v171
	v_cvt_pk_bf16_f32 v76, v168, v170
	v_cvt_pk_bf16_f32 v48, v48, v50
	s_waitcnt lgkmcnt(1)
	v_mfma_f32_32x32x16_bf16 v[32:47], v[160:163], v[70:73], v[32:47]
	v_cvt_pk_bf16_f32 v49, v59, v65
	v_cvt_pk_bf16_f32 v53, v58, v64
	v_cvt_pk_bf16_f32 v50, v51, v55
	v_cvt_pk_bf16_f32 v51, v56, v66
	v_cvt_pk_bf16_f32 v55, v60, v68
	ds_read_b128 v[56:59], v2 offset:15904
	ds_read_b128 v[60:63], v2 offset:11360
	ds_read_b128 v[64:67], v2 offset:15968
	v_cvt_pk_bf16_f32 v52, v52, v54
	v_mfma_f32_32x32x16_bf16 v[16:31], v[138:141], v[70:73], v[16:31]
	v_cvt_pk_bf16_f32 v54, v146, v147
	v_mov_b32_e32 v191, v1
	v_mov_b32_e32 v160, v0
	v_mfma_f32_32x32x16_bf16 v[32:47], v[142:145], v[74:77], v[32:47]
	v_mfma_f32_32x32x16_bf16 v[16:31], v[150:153], v[74:77], v[16:31]
	s_waitcnt lgkmcnt(3)
	v_mfma_f32_32x32x16_bf16 v[32:47], v[164:167], v[48:51], v[32:47]
	s_waitcnt lgkmcnt(2)
	v_mfma_f32_32x32x16_bf16 v[16:31], v[56:59], v[48:51], v[16:31]
	s_waitcnt lgkmcnt(1)
	v_mfma_f32_32x32x16_bf16 v[32:47], v[60:63], v[52:55], v[32:47]
	s_waitcnt lgkmcnt(0)
	v_mfma_f32_32x32x16_bf16 v[16:31], v[64:67], v[52:55], v[16:31]
